# m1 FoX body + GEMM: first two counted waits of each tile no longer drain the previous epilogue's stores (vmcnt 8 -> 8+stores)
# speedup vs baseline: 1.0182x; 1.0092x over previous
; #define PG8_STAGE(bufoff, gbase, voff) do { _Pragma("unroll") for (int _i = 0; _i < 2; ++_i) \
;         __builtin_amdgcn_global_load_lds((const unsigned*)((const char*)(gbase) + (voff)[_i]), (PG8_LAS unsigned*)(lds + (bufoff) + ldsw + _i * 8192), 16, 0, 0); } while (0)
; #define PG8_WAIT_V(n) asm volatile("s_waitcnt vmcnt(" #n ")" ::: "memory")
; #define PG8_BAR __builtin_amdgcn_s_barrier()
; template <class Epi, class Sched, bool ALIGN_EPI = false, bool SP2 = false>
; __device__ __forceinline__ void gemm_phase(PG8_LAS unsigned char* lds, const Gemm g, const Sched& S, const Epi& E, const int tid) {
;     ...
;         PG8_STAGE(PG8_SB(1, 0), cB + kstep, voffB); PG8_STAGE(PG8_SA(1, 0), cA + kstep, voffA); PG8_STAGE(PG8_SB(1, 1), cB + hstep + kstep, voffB);
;         PG8_WAIT_V(6); PG8_BAR;
;     ...
;     for (;;) {
;         const bool has_next = S.next(ui + 1, nxt);
;         const char* nA = has_next ? (const char*)g.A + (size_t)nxt.pm * tstep : cA; const char* nB = has_next ? (const char*)g.Bt + (size_t)nxt.pn * tstep : cB;
;         for (int t = 0; t < nt; t += 2) {
;             const bool last = (t == nt - 2);
;             const char* a1 = cA + (size_t)(t + 1) * kstep;
;             const char* a2 = last ? nA : cA + (size_t)(t + 2) * kstep; const char* b2 = last ? nB : cB + (size_t)(t + 2) * kstep;
;             const char* a3 = a2 + kstep; const char* b3 = b2 + kstep;
;             if (last && has_next) S.a_ready(nxt);
.LBB0_222:
	s_mov_b64 s[10:11], 0x80
	s_and_b32 s7, s0, 3
	s_add_i32 m0, s15, 0x18000
	v_lshl_add_u64 v[6:7], v[6:7], 0, s[10:11]
	s_lshl_b32 s14, s1, 6
	s_lshl_b32 s13, s1, 13
	s_lshl_b32 s18, s7, 5
	s_lshl_b32 s7, s7, 12
	s_waitcnt vmcnt(2)
	s_barrier
	global_load_lds_dwordx4 v[6:7], off
	v_lshl_add_u64 v[4:5], v[4:5], 0, s[10:11]
	s_add_i32 m0, s15, 0x1a000
	s_add_i32 s44, s15, 0x8000
	s_add_i32 s45, s15, 0xa000
	global_load_lds_dwordx4 v[4:5], off
	v_lshl_add_u64 v[0:1], v[0:1], 0, s[10:11]
	s_mov_b32 m0, s44
	s_add_u32 s16, s24, 0x40080
	global_load_lds_dwordx4 v[0:1], off
	v_lshl_add_u64 v[0:1], v[2:3], 0, s[10:11]
	s_mov_b32 m0, s45
	s_addc_u32 s17, s25, 0
	global_load_lds_dwordx4 v[0:1], off
	s_add_i32 m0, s15, 0x1c000
	v_lshl_add_u64 v[0:1], s[16:17], 0, v[138:139]
	global_load_lds_dwordx4 v[0:1], off
	v_lshl_add_u64 v[0:1], s[16:17], 0, v[142:143]
	s_add_i32 m0, s15, 0x1e000
	v_lshlrev_b32_e32 v2, 6, v156
	global_load_lds_dwordx4 v[0:1], off
	v_lshrrev_b32_e32 v0, 1, v19
	v_and_b32_e32 v0, 24, v0
	v_lshlrev_b32_e32 v1, 1, v0
	s_movk_i32 s16, 0x3c0
	v_lshlrev_b32_e32 v4, 2, v156
	v_and_or_b32 v3, v2, s16, v1
	v_and_b32_e32 v4, 32, v4
	s_cmpk_lt_u32 s12, 0x100
	v_bitop3_b32 v3, v3, s13, v4 bitop3:0xde
	s_cselect_b64 s[12:13], -1, 0
	s_add_u32 s46, s92, 0xc800000
	s_addc_u32 s47, s93, 0
	s_bfe_u32 s48, s0, 0x10001
	s_lshl_b32 s0, s1, 4
	s_and_b32 s49, s0, 0x3fffff0
	s_or_b32 s0, s14, 32
	v_or_b32_e32 v160, s0, v156
	s_lshr_b32 s0, s0, 2
	s_and_b32 s50, s0, 0x3fffff8
	s_or_b32 s0, s14, 48
	v_or_b32_e32 v161, s0, v156
	s_lshr_b32 s0, s0, 2
	s_and_b32 s51, s0, 0x3fffff8
	s_add_i32 s0, s14, 0x80
	v_or_b32_e32 v166, s18, v0
	v_and_or_b32 v167, s18, 32, v0
	v_lshlrev_b32_e32 v0, 14, v8
	v_or_b32_e32 v1, v1, v2
	v_or_b32_e32 v162, s0, v156
	s_lshr_b32 s0, s0, 2
	v_and_b32_e32 v0, 0xffff8000, v0
	v_bitop3_b32 v158, s7, v1, v4 bitop3:0xf6
	s_and_b32 s52, s0, 0x3fffff0
	s_add_i32 s0, s14, 0x90
	v_lshl_add_u32 v0, v9, 11, v0
	v_and_b32_e32 v1, 1, v8
	v_or_b32_e32 v163, s0, v156
	s_lshr_b32 s0, s0, 2
	v_lshl_or_b32 v0, v1, 6, v0
	s_and_b32 s53, s0, 0x3fffff0
	s_add_i32 s0, s14, 0xa0
	v_lshl_add_u32 v146, v10, 1, v0
	v_lshlrev_b32_e32 v0, 14, v11
	v_or_b32_e32 v157, s14, v156
	v_or_b32_e32 v164, s0, v156
	s_lshr_b32 s0, s0, 2
	s_addk_i32 s14, 0xb0
	v_and_b32_e32 v0, 0xffff8000, v0
	s_waitcnt vmcnt(6)
	s_and_b32 s54, s0, 0x3fffff8
	s_lshr_b32 s0, s14, 2
	v_lshl_add_u32 v0, v12, 11, v0
	v_and_b32_e32 v1, 1, v11
	s_and_b32 s55, s0, 0x3fffff8
	v_readlane_b32 s0, v241, 7
	v_lshl_or_b32 v0, v1, 6, v0
	s_add_i32 s59, 0, 0x10000
	s_add_i32 s60, 0, 0x14000
	v_or_b32_e32 v159, 16, v157
	v_or_b32_e32 v165, s14, v156
	s_ashr_i32 s56, s94, 31
	s_mov_b32 s57, s94
	s_ashr_i32 s58, s0, 31
	v_mov_b32_e32 v147, v145
	v_lshl_add_u32 v148, v13, 1, v0
	v_mov_b32_e32 v149, v145
	v_mov_b64_e32 v[150:151], 0x1000
	v_mov_b64_e32 v[152:153], 0xfff
	v_add_u32_e32 v168, s59, v158
	v_add_u32_e32 v169, s60, v158
	v_add_u32_e32 v170, 0, v3
	s_mov_b32 s61, 0x1c00000
	s_mov_b32 s62, 0x1200000
	s_mov_b32 s63, 0x90c0000
	s_mov_b32 s64, 0x9100000
	s_mov_b32 s65, 0x10100000
	s_mov_b32 s66, 0x14100000
	s_mov_b32 s14, 0x3e38aa3b
	s_barrier
	s_mov_b32 s32, 0
	s_branch .LBB0_225
.Lg1w1_x:
	s_cmp_eq_u32 s32, 24
	s_cbranch_scc1 .Lg1w1_24
	s_waitcnt vmcnt(56)
	s_branch .Lg1w1_j
.Lg1w1_24:
	s_waitcnt vmcnt(24)
	s_branch .Lg1w1_j
.Lg1w2_x:
	s_cmp_eq_u32 s32, 24
	s_cbranch_scc1 .Lg1w2_24
	s_waitcnt vmcnt(56)
	s_mov_b32 s32, 0
	s_branch .Lg1w2_j
.Lg1w2_24:
	s_waitcnt vmcnt(24)
	s_mov_b32 s32, 0
	s_branch .Lg1w2_j

; #define PG8_STAGE(bufoff, gbase, voff) do { _Pragma("unroll") for (int _i = 0; _i < 2; ++_i) \
;         __builtin_amdgcn_global_load_lds((const unsigned*)((const char*)(gbase) + (voff)[_i]), (PG8_LAS unsigned*)(lds + (bufoff) + ldsw + _i * 8192), 16, 0, 0); } while (0)
; #define PG8_LDA(dst, b, h) do { _Pragma("unroll") for (int m = 0; m < 4; ++m) _Pragma("unroll") for (int k = 0; k < 2; ++k) dst[m][k] = *(const PG8_LAS bf16x8*)(lds + PG8_SA(b, h) + aoff + m * 2048 + k * 1024); } while (0)
; #define PG8_LDB(dst, b, h) do { _Pragma("unroll") for (int n = 0; n < 2; ++n) _Pragma("unroll") for (int k = 0; k < 2; ++k) dst[n][k] = *(const PG8_LAS bf16x8*)(lds + PG8_SB(b, h) + boff + n * 2048 + k * 1024); } while (0)
; #define PG8_MMA(ai, bj, At, Bt) do { __builtin_amdgcn_s_setprio(1); _Pragma("unroll") for (int m = 0; m < 4; ++m) _Pragma("unroll") for (int n = 0; n < 2; ++n) _Pragma("unroll") for (int k = 0; k < 2; ++k) \
;         acc[ai][bj][m][n] = __builtin_amdgcn_mfma_f32_16x16x32_bf16(Bt[n][k], At[m][k], acc[ai][bj][m][n], 0, 0, 0); __builtin_amdgcn_s_setprio(0); } while (0)
; #define PG8_WAIT_V(n) asm volatile("s_waitcnt vmcnt(" #n ")" ::: "memory")
; #define PG8_WAIT_L(n) asm volatile("s_waitcnt lgkmcnt(" #n ")" ::: "memory")
; #define PG8_BAR __builtin_amdgcn_s_barrier()
; #define PG8_SCHED __builtin_amdgcn_sched_barrier(0)
; template <class Epi, class Sched, bool ALIGN_EPI = false, bool SP2 = false>
; __device__ __forceinline__ void gemm_phase(PG8_LAS unsigned char* lds, const Gemm g, const Sched& S, const Epi& E, const int tid) {
;     ...
;             PG8_LDB(B0, 0, 0); PG8_LDB(B1, 0, 1); PG8_SCHED; PG8_LDA(At, 0, 0); PG8_STAGE(PG8_SA(1, 1), a1 + hstep, voffA);
;             PG8_WAIT_V(8); PG8_WAIT_L(0); PG8_BAR; PG8_MMA(0, 0, At, B0); PG8_MMA(0, 1, At, B1); PG8_BAR; PG8_SCHED;
;             PG8_LDA(At, 0, 1); PG8_STAGE(PG8_SB(0, 0), b2, voffB); PG8_STAGE(PG8_SB(0, 1), b2 + hstep, voffB); PG8_STAGE(PG8_SA(0, 0), a2, voffA);
;             PG8_WAIT_V(8); PG8_WAIT_L(0); PG8_BAR; PG8_MMA(1, 0, At, B0); PG8_MMA(1, 1, At, B1); PG8_BAR; PG8_SCHED;
.LBB0_232:
	ds_read_b128 v[128:131], v168
	ds_read_b128 v[132:135], v168 offset:1024
	ds_read_b128 v[172:175], v168 offset:2048
	ds_read_b128 v[180:183], v168 offset:3072
	ds_read_b128 v[186:189], v169
	ds_read_b128 v[190:193], v169 offset:1024
	ds_read_b128 v[194:197], v169 offset:2048
	ds_read_b128 v[198:201], v169 offset:3072
	s_add_u32 s24, s4, 0xfffc0080
	s_addc_u32 s25, s5, -1
	s_cmp_eq_u32 s33, 12
	s_cselect_b32 s27, s7, s25
	s_cselect_b32 s26, s19, s24
	s_cselect_b32 s25, s17, s31
	s_cselect_b32 s24, s29, s30
	v_lshl_add_u64 v[154:155], s[4:5], 0, v[146:147]
	s_add_i32 m0, s15, 0xc000
	ds_read_b128 v[202:205], v170
	ds_read_b128 v[206:209], v170 offset:1024
	ds_read_b128 v[210:213], v170 offset:2048
	ds_read_b128 v[214:217], v170 offset:3072
	ds_read_b128 v[218:221], v170 offset:4096
	ds_read_b128 v[222:225], v170 offset:5120
	ds_read_b128 v[226:229], v170 offset:6144
	ds_read_b128 v[230:233], v170 offset:7168
	global_load_lds_dwordx4 v[154:155], off
	v_lshl_add_u64 v[154:155], s[4:5], 0, v[148:149]
	s_add_i32 m0, s15, 0xe000
	s_nop 0
	global_load_lds_dwordx4 v[154:155], off
	s_cmp_lg_u32 s32, 0
	s_cbranch_scc1 .Lg1w1_x
	s_waitcnt vmcnt(8)
.Lg1w1_j:
	s_waitcnt lgkmcnt(0)
	s_barrier
	s_setprio 1
	s_waitcnt lgkmcnt(0)
	v_mfma_f32_16x16x32_bf16 v[124:127], v[128:131], v[202:205], v[124:127]
	v_mfma_f32_16x16x32_bf16 v[120:123], v[172:175], v[202:205], v[120:123]
	v_mfma_f32_16x16x32_bf16 v[108:111], v[128:131], v[210:213], v[108:111]
	v_mfma_f32_16x16x32_bf16 v[104:107], v[172:175], v[210:213], v[104:107]
	v_mfma_f32_16x16x32_bf16 v[92:95], v[128:131], v[218:221], v[92:95]
	v_mfma_f32_16x16x32_bf16 v[88:91], v[172:175], v[218:221], v[88:91]
	v_mfma_f32_16x16x32_bf16 v[76:79], v[128:131], v[226:229], v[76:79]
	v_mfma_f32_16x16x32_bf16 v[72:75], v[172:175], v[226:229], v[72:75]
	v_mfma_f32_16x16x32_bf16 v[124:127], v[132:135], v[206:209], v[124:127]
	v_mfma_f32_16x16x32_bf16 v[120:123], v[180:183], v[206:209], v[120:123]
	v_mfma_f32_16x16x32_bf16 v[108:111], v[132:135], v[214:217], v[108:111]
	v_mfma_f32_16x16x32_bf16 v[104:107], v[180:183], v[214:217], v[104:107]
	v_mfma_f32_16x16x32_bf16 v[92:95], v[132:135], v[222:225], v[92:95]
	v_mfma_f32_16x16x32_bf16 v[88:91], v[180:183], v[222:225], v[88:91]
	v_mfma_f32_16x16x32_bf16 v[76:79], v[132:135], v[230:233], v[76:79]
	v_mfma_f32_16x16x32_bf16 v[72:75], v[180:183], v[230:233], v[72:75]
	s_setprio 0
	s_setprio 1
	v_mfma_f32_16x16x32_bf16 v[116:119], v[186:189], v[202:205], v[116:119]
	v_mfma_f32_16x16x32_bf16 v[112:115], v[194:197], v[202:205], v[112:115]
	v_mfma_f32_16x16x32_bf16 v[100:103], v[186:189], v[210:213], v[100:103]
	v_mfma_f32_16x16x32_bf16 v[96:99], v[194:197], v[210:213], v[96:99]
	v_mfma_f32_16x16x32_bf16 v[84:87], v[186:189], v[218:221], v[84:87]
	v_mfma_f32_16x16x32_bf16 v[80:83], v[194:197], v[218:221], v[80:83]
	v_mfma_f32_16x16x32_bf16 v[68:71], v[186:189], v[226:229], v[68:71]
	v_mfma_f32_16x16x32_bf16 v[64:67], v[194:197], v[226:229], v[64:67]
	v_mfma_f32_16x16x32_bf16 v[116:119], v[190:193], v[206:209], v[116:119]
	v_mfma_f32_16x16x32_bf16 v[112:115], v[198:201], v[206:209], v[112:115]
	v_mfma_f32_16x16x32_bf16 v[100:103], v[190:193], v[214:217], v[100:103]
	v_mfma_f32_16x16x32_bf16 v[96:99], v[198:201], v[214:217], v[96:99]
	v_mfma_f32_16x16x32_bf16 v[84:87], v[190:193], v[222:225], v[84:87]
	v_mfma_f32_16x16x32_bf16 v[80:83], v[198:201], v[222:225], v[80:83]
	v_mfma_f32_16x16x32_bf16 v[68:71], v[190:193], v[230:233], v[68:71]
	v_mfma_f32_16x16x32_bf16 v[64:67], v[198:201], v[230:233], v[64:67]
	s_setprio 0
	s_barrier
	s_add_i32 s34, s59, s3
	v_lshl_add_u64 v[154:155], s[24:25], 0, v[138:139]
	s_mov_b32 m0, s34
	ds_read_b128 v[202:205], v170 offset:16384
	ds_read_b128 v[206:209], v170 offset:17408
	ds_read_b128 v[210:213], v170 offset:18432
	ds_read_b128 v[214:217], v170 offset:19456
	ds_read_b128 v[218:221], v170 offset:20480
	ds_read_b128 v[222:225], v170 offset:21504
	ds_read_b128 v[226:229], v170 offset:22528
	ds_read_b128 v[230:233], v170 offset:23552
	global_load_lds_dwordx4 v[154:155], off
	s_add_i32 m0, s34, 0x2000
	s_add_u32 s34, s24, 0x40000
	v_lshl_add_u64 v[176:177], s[24:25], 0, v[142:143]
	s_addc_u32 s35, s25, 0
	s_add_i32 s36, s60, s3
	global_load_lds_dwordx4 v[176:177], off
	v_lshl_add_u64 v[234:235], s[34:35], 0, v[138:139]
	s_mov_b32 m0, s36
	v_lshl_add_u64 v[236:237], s[26:27], 0, v[140:141]
	global_load_lds_dwordx4 v[234:235], off
	v_lshl_add_u64 v[234:235], s[34:35], 0, v[142:143]
	s_add_i32 m0, s36, 0x2000
	s_nop 0
	global_load_lds_dwordx4 v[234:235], off
	v_lshl_add_u64 v[234:235], s[26:27], 0, v[136:137]
	s_mov_b32 m0, s15
	s_nop 0
	global_load_lds_dwordx4 v[234:235], off
	s_mov_b32 m0, s38
	s_nop 0
	global_load_lds_dwordx4 v[236:237], off
	s_cmp_lg_u32 s32, 0
	s_cbranch_scc1 .Lg1w2_x
	s_waitcnt vmcnt(8)
; #define PG8_STAGE(bufoff, gbase, voff) do { _Pragma("unroll") for (int _i = 0; _i < 2; ++_i) \
;         __builtin_amdgcn_global_load_lds((const unsigned*)((const char*)(gbase) + (voff)[_i]), (PG8_LAS unsigned*)(lds + (bufoff) + ldsw + _i * 8192), 16, 0, 0); } while (0)
; #define PG8_LDA(dst, b, h) do { _Pragma("unroll") for (int m = 0; m < 4; ++m) _Pragma("unroll") for (int k = 0; k < 2; ++k) dst[m][k] = *(const PG8_LAS bf16x8*)(lds + PG8_SA(b, h) + aoff + m * 2048 + k * 1024); } while (0)
; #define PG8_LDB(dst, b, h) do { _Pragma("unroll") for (int n = 0; n < 2; ++n) _Pragma("unroll") for (int k = 0; k < 2; ++k) dst[n][k] = *(const PG8_LAS bf16x8*)(lds + PG8_SB(b, h) + boff + n * 2048 + k * 1024); } while (0)
; #define PG8_MMA(ai, bj, At, Bt) do { __builtin_amdgcn_s_setprio(1); _Pragma("unroll") for (int m = 0; m < 4; ++m) _Pragma("unroll") for (int n = 0; n < 2; ++n) _Pragma("unroll") for (int k = 0; k < 2; ++k) \
;         acc[ai][bj][m][n] = __builtin_amdgcn_mfma_f32_16x16x32_bf16(Bt[n][k], At[m][k], acc[ai][bj][m][n], 0, 0, 0); __builtin_amdgcn_s_setprio(0); } while (0)
; #define PG8_WAIT_V(n) asm volatile("s_waitcnt vmcnt(" #n ")" ::: "memory")
; #define PG8_WAIT_L(n) asm volatile("s_waitcnt lgkmcnt(" #n ")" ::: "memory")
; #define PG8_BAR __builtin_amdgcn_s_barrier()
; #define PG8_SCHED __builtin_amdgcn_sched_barrier(0)
; template <class Epi, class Sched, bool ALIGN_EPI = false, bool SP2 = false>
; __device__ __forceinline__ void gemm_phase(PG8_LAS unsigned char* lds, const Gemm g, const Sched& S, const Epi& E, const int tid) {
;     ...
;             PG8_WAIT_V(8); PG8_WAIT_L(0); PG8_BAR; PG8_MMA(1, 0, At, B0); PG8_MMA(1, 1, At, B1); PG8_BAR; PG8_SCHED;
;             PG8_LDB(B0, 1, 0); PG8_LDB(B1, 1, 1); PG8_SCHED; PG8_LDA(At, 1, 0); PG8_STAGE(PG8_SA(0, 1), a2 + hstep, voffA);
;             PG8_WAIT_V(8); PG8_WAIT_L(0); PG8_BAR; PG8_MMA(0, 0, At, B0); PG8_MMA(0, 1, At, B1); PG8_BAR; PG8_SCHED;
.Lg1w2_j:
	s_waitcnt lgkmcnt(0)
	s_barrier
	s_setprio 1
	s_waitcnt lgkmcnt(0)
	v_mfma_f32_16x16x32_bf16 v[60:63], v[128:131], v[202:205], v[60:63]
	v_mfma_f32_16x16x32_bf16 v[56:59], v[172:175], v[202:205], v[56:59]
	v_mfma_f32_16x16x32_bf16 v[44:47], v[128:131], v[210:213], v[44:47]
	v_mfma_f32_16x16x32_bf16 v[40:43], v[172:175], v[210:213], v[40:43]
	v_mfma_f32_16x16x32_bf16 v[28:31], v[128:131], v[218:221], v[28:31]
	v_mfma_f32_16x16x32_bf16 v[24:27], v[172:175], v[218:221], v[24:27]
	v_mfma_f32_16x16x32_bf16 v[12:15], v[128:131], v[226:229], v[12:15]
	v_mfma_f32_16x16x32_bf16 v[8:11], v[172:175], v[226:229], v[8:11]
	v_mfma_f32_16x16x32_bf16 v[60:63], v[132:135], v[206:209], v[60:63]
	v_mfma_f32_16x16x32_bf16 v[56:59], v[180:183], v[206:209], v[56:59]
	v_mfma_f32_16x16x32_bf16 v[44:47], v[132:135], v[214:217], v[44:47]
	v_mfma_f32_16x16x32_bf16 v[40:43], v[180:183], v[214:217], v[40:43]
	v_mfma_f32_16x16x32_bf16 v[28:31], v[132:135], v[222:225], v[28:31]
	v_mfma_f32_16x16x32_bf16 v[24:27], v[180:183], v[222:225], v[24:27]
	v_mfma_f32_16x16x32_bf16 v[12:15], v[132:135], v[230:233], v[12:15]
	v_mfma_f32_16x16x32_bf16 v[8:11], v[180:183], v[230:233], v[8:11]
	s_setprio 0
	s_setprio 1
	v_mfma_f32_16x16x32_bf16 v[52:55], v[186:189], v[202:205], v[52:55]
	v_mfma_f32_16x16x32_bf16 v[48:51], v[194:197], v[202:205], v[48:51]
	v_mfma_f32_16x16x32_bf16 v[36:39], v[186:189], v[210:213], v[36:39]
	v_mfma_f32_16x16x32_bf16 v[32:35], v[194:197], v[210:213], v[32:35]
	v_mfma_f32_16x16x32_bf16 v[20:23], v[186:189], v[218:221], v[20:23]
	v_mfma_f32_16x16x32_bf16 v[16:19], v[194:197], v[218:221], v[16:19]
	v_mfma_f32_16x16x32_bf16 v[4:7], v[186:189], v[226:229], v[4:7]
	v_mfma_f32_16x16x32_bf16 v[0:3], v[194:197], v[226:229], v[0:3]
	v_mfma_f32_16x16x32_bf16 v[52:55], v[190:193], v[206:209], v[52:55]
	v_mfma_f32_16x16x32_bf16 v[48:51], v[198:201], v[206:209], v[48:51]
	v_mfma_f32_16x16x32_bf16 v[36:39], v[190:193], v[214:217], v[36:39]
	v_mfma_f32_16x16x32_bf16 v[32:35], v[198:201], v[214:217], v[32:35]
	v_mfma_f32_16x16x32_bf16 v[20:23], v[190:193], v[222:225], v[20:23]
	v_mfma_f32_16x16x32_bf16 v[16:19], v[198:201], v[222:225], v[16:19]
	v_mfma_f32_16x16x32_bf16 v[4:7], v[190:193], v[230:233], v[4:7]
	v_mfma_f32_16x16x32_bf16 v[0:3], v[198:201], v[230:233], v[0:3]
	s_setprio 0
	s_barrier
	s_add_i32 s34, 0, 0x18000
	v_add_u32_e32 v144, s34, v158
	s_add_i32 s35, 0, 0x1c000
	ds_read_b128 v[128:131], v144
	ds_read_b128 v[132:135], v144 offset:1024
	ds_read_b128 v[172:175], v144 offset:2048
	ds_read_b128 v[180:183], v144 offset:3072
	v_add_u32_e32 v144, s35, v158
	ds_read_b128 v[186:189], v144
	ds_read_b128 v[190:193], v144 offset:1024
	ds_read_b128 v[194:197], v144 offset:2048
	ds_read_b128 v[198:201], v144 offset:3072
	s_add_u32 s26, s26, 0x40000
	s_addc_u32 s27, s27, 0
	s_mov_b32 m0, s39
	v_lshl_add_u64 v[238:239], s[26:27], 0, v[136:137]
	ds_read_b128 v[202:205], v170 offset:32768
	ds_read_b128 v[206:209], v170 offset:33792
	ds_read_b128 v[210:213], v170 offset:34816
	ds_read_b128 v[214:217], v170 offset:35840
	ds_read_b128 v[218:221], v170 offset:36864
	ds_read_b128 v[222:225], v170 offset:37888
	ds_read_b128 v[226:229], v170 offset:38912
	ds_read_b128 v[230:233], v170 offset:39936
	global_load_lds_dwordx4 v[238:239], off
	v_lshl_add_u64 v[238:239], s[26:27], 0, v[140:141]
	s_mov_b32 m0, s42
	s_nop 0
	global_load_lds_dwordx4 v[238:239], off
	s_waitcnt vmcnt(8)
	s_waitcnt lgkmcnt(0)
	s_barrier
	s_setprio 1
	s_waitcnt lgkmcnt(0)
	v_mfma_f32_16x16x32_bf16 v[124:127], v[128:131], v[202:205], v[124:127]
	v_mfma_f32_16x16x32_bf16 v[120:123], v[172:175], v[202:205], v[120:123]
	v_mfma_f32_16x16x32_bf16 v[108:111], v[128:131], v[210:213], v[108:111]
	v_mfma_f32_16x16x32_bf16 v[104:107], v[172:175], v[210:213], v[104:107]
	v_mfma_f32_16x16x32_bf16 v[92:95], v[128:131], v[218:221], v[92:95]
	v_mfma_f32_16x16x32_bf16 v[88:91], v[172:175], v[218:221], v[88:91]
	v_mfma_f32_16x16x32_bf16 v[76:79], v[128:131], v[226:229], v[76:79]
	v_mfma_f32_16x16x32_bf16 v[72:75], v[172:175], v[226:229], v[72:75]
	v_mfma_f32_16x16x32_bf16 v[124:127], v[132:135], v[206:209], v[124:127]
	v_mfma_f32_16x16x32_bf16 v[120:123], v[180:183], v[206:209], v[120:123]
	v_mfma_f32_16x16x32_bf16 v[108:111], v[132:135], v[214:217], v[108:111]
	v_mfma_f32_16x16x32_bf16 v[104:107], v[180:183], v[214:217], v[104:107]
	v_mfma_f32_16x16x32_bf16 v[92:95], v[132:135], v[222:225], v[92:95]
	v_mfma_f32_16x16x32_bf16 v[88:91], v[180:183], v[222:225], v[88:91]
	v_mfma_f32_16x16x32_bf16 v[76:79], v[132:135], v[230:233], v[76:79]
	v_mfma_f32_16x16x32_bf16 v[72:75], v[180:183], v[230:233], v[72:75]
	s_setprio 0
	s_setprio 1
	v_mfma_f32_16x16x32_bf16 v[116:119], v[186:189], v[202:205], v[116:119]
	v_mfma_f32_16x16x32_bf16 v[112:115], v[194:197], v[202:205], v[112:115]
	v_mfma_f32_16x16x32_bf16 v[100:103], v[186:189], v[210:213], v[100:103]
	v_mfma_f32_16x16x32_bf16 v[96:99], v[194:197], v[210:213], v[96:99]
	v_mfma_f32_16x16x32_bf16 v[84:87], v[186:189], v[218:221], v[84:87]
	v_mfma_f32_16x16x32_bf16 v[80:83], v[194:197], v[218:221], v[80:83]
	v_mfma_f32_16x16x32_bf16 v[68:71], v[186:189], v[226:229], v[68:71]
	v_mfma_f32_16x16x32_bf16 v[64:67], v[194:197], v[226:229], v[64:67]
	v_mfma_f32_16x16x32_bf16 v[116:119], v[190:193], v[206:209], v[116:119]
	v_mfma_f32_16x16x32_bf16 v[112:115], v[198:201], v[206:209], v[112:115]
	v_mfma_f32_16x16x32_bf16 v[100:103], v[190:193], v[214:217], v[100:103]
	v_mfma_f32_16x16x32_bf16 v[96:99], v[198:201], v[214:217], v[96:99]
	v_mfma_f32_16x16x32_bf16 v[84:87], v[190:193], v[222:225], v[84:87]
	v_mfma_f32_16x16x32_bf16 v[80:83], v[198:201], v[222:225], v[80:83]
	v_mfma_f32_16x16x32_bf16 v[68:71], v[190:193], v[230:233], v[68:71]
	v_mfma_f32_16x16x32_bf16 v[64:67], v[198:201], v[230:233], v[64:67]
	s_setprio 0
	s_barrier
; #define PG8_STAGE(bufoff, gbase, voff) do { _Pragma("unroll") for (int _i = 0; _i < 2; ++_i) \
;         __builtin_amdgcn_global_load_lds((const unsigned*)((const char*)(gbase) + (voff)[_i]), (PG8_LAS unsigned*)(lds + (bufoff) + ldsw + _i * 8192), 16, 0, 0); } while (0)
; #define PG8_LDA(dst, b, h) do { _Pragma("unroll") for (int m = 0; m < 4; ++m) _Pragma("unroll") for (int k = 0; k < 2; ++k) dst[m][k] = *(const PG8_LAS bf16x8*)(lds + PG8_SA(b, h) + aoff + m * 2048 + k * 1024); } while (0)
; #define PG8_MMA(ai, bj, At, Bt) do { __builtin_amdgcn_s_setprio(1); _Pragma("unroll") for (int m = 0; m < 4; ++m) _Pragma("unroll") for (int n = 0; n < 2; ++n) _Pragma("unroll") for (int k = 0; k < 2; ++k) \
;         acc[ai][bj][m][n] = __builtin_amdgcn_mfma_f32_16x16x32_bf16(Bt[n][k], At[m][k], acc[ai][bj][m][n], 0, 0, 0); __builtin_amdgcn_s_setprio(0); } while (0)
; #define PG8_WAIT_V(n) asm volatile("s_waitcnt vmcnt(" #n ")" ::: "memory")
; #define PG8_WAIT_L(n) asm volatile("s_waitcnt lgkmcnt(" #n ")" ::: "memory")
; #define PG8_BAR __builtin_amdgcn_s_barrier()
; #define PG8_SCHED __builtin_amdgcn_sched_barrier(0)
; template <class Epi, class Sched, bool ALIGN_EPI = false, bool SP2 = false>
; __device__ __forceinline__ void gemm_phase(PG8_LAS unsigned char* lds, const Gemm g, const Sched& S, const Epi& E, const int tid) {
;     ...
;         for (int t = 0; t < nt; t += 2) {
;     ...
;             PG8_LDA(At, 1, 1); PG8_STAGE(PG8_SB(1, 0), b3, voffB); PG8_STAGE(PG8_SB(1, 1), b3 + hstep, voffB); PG8_STAGE(PG8_SA(1, 0), a3, voffA);
;             PG8_WAIT_V(8); PG8_WAIT_L(0); PG8_BAR; PG8_MMA(1, 0, At, B0); PG8_MMA(1, 1, At, B1); PG8_BAR; PG8_SCHED;
	s_add_i32 s26, s34, s3
	v_lshl_add_u64 v[154:155], v[154:155], 0, s[10:11]
	s_mov_b32 m0, s26
	ds_read_b128 v[202:205], v170 offset:49152
	ds_read_b128 v[206:209], v170 offset:50176
	ds_read_b128 v[210:213], v170 offset:51200
	ds_read_b128 v[214:217], v170 offset:52224
	ds_read_b128 v[218:221], v170 offset:53248
	ds_read_b128 v[222:225], v170 offset:54272
	ds_read_b128 v[226:229], v170 offset:55296
	ds_read_b128 v[230:233], v170 offset:56320
	global_load_lds_dwordx4 v[154:155], off
	s_add_i32 m0, s26, 0x2000
	s_add_u32 s24, s24, 0x40080
	v_lshl_add_u64 v[154:155], v[176:177], 0, s[10:11]
	s_addc_u32 s25, s25, 0
	s_add_i32 s26, s35, s3
	global_load_lds_dwordx4 v[154:155], off
	v_lshl_add_u64 v[154:155], s[24:25], 0, v[138:139]
	s_mov_b32 m0, s26
	s_nop 0
	global_load_lds_dwordx4 v[154:155], off
	v_lshl_add_u64 v[154:155], s[24:25], 0, v[142:143]
	s_add_i32 m0, s26, 0x2000
	s_nop 0
	global_load_lds_dwordx4 v[154:155], off
	v_lshl_add_u64 v[154:155], v[234:235], 0, s[10:11]
	s_mov_b32 m0, s44
	s_nop 0
	global_load_lds_dwordx4 v[154:155], off
	v_lshl_add_u64 v[154:155], v[236:237], 0, s[10:11]
	s_mov_b32 m0, s45
	s_nop 0
	global_load_lds_dwordx4 v[154:155], off
	s_waitcnt vmcnt(8)
	s_waitcnt lgkmcnt(0)
	s_barrier
	s_setprio 1
	s_waitcnt lgkmcnt(0)
	v_mfma_f32_16x16x32_bf16 v[60:63], v[128:131], v[202:205], v[60:63]
	v_mfma_f32_16x16x32_bf16 v[56:59], v[172:175], v[202:205], v[56:59]
	v_mfma_f32_16x16x32_bf16 v[44:47], v[128:131], v[210:213], v[44:47]
	v_mfma_f32_16x16x32_bf16 v[40:43], v[172:175], v[210:213], v[40:43]
	v_mfma_f32_16x16x32_bf16 v[28:31], v[128:131], v[218:221], v[28:31]
	v_mfma_f32_16x16x32_bf16 v[24:27], v[172:175], v[218:221], v[24:27]
	v_mfma_f32_16x16x32_bf16 v[12:15], v[128:131], v[226:229], v[12:15]
	v_mfma_f32_16x16x32_bf16 v[8:11], v[172:175], v[226:229], v[8:11]
	v_mfma_f32_16x16x32_bf16 v[60:63], v[132:135], v[206:209], v[60:63]
	v_mfma_f32_16x16x32_bf16 v[56:59], v[180:183], v[206:209], v[56:59]
	v_mfma_f32_16x16x32_bf16 v[44:47], v[132:135], v[214:217], v[44:47]
	v_mfma_f32_16x16x32_bf16 v[40:43], v[180:183], v[214:217], v[40:43]
	v_mfma_f32_16x16x32_bf16 v[28:31], v[132:135], v[222:225], v[28:31]
	v_mfma_f32_16x16x32_bf16 v[24:27], v[180:183], v[222:225], v[24:27]
	v_mfma_f32_16x16x32_bf16 v[12:15], v[132:135], v[230:233], v[12:15]
	v_mfma_f32_16x16x32_bf16 v[8:11], v[180:183], v[230:233], v[8:11]
	s_setprio 0
	s_setprio 1
	v_mfma_f32_16x16x32_bf16 v[52:55], v[186:189], v[202:205], v[52:55]
	v_mfma_f32_16x16x32_bf16 v[48:51], v[194:197], v[202:205], v[48:51]
	v_mfma_f32_16x16x32_bf16 v[36:39], v[186:189], v[210:213], v[36:39]
	v_mfma_f32_16x16x32_bf16 v[32:35], v[194:197], v[210:213], v[32:35]
	v_mfma_f32_16x16x32_bf16 v[20:23], v[186:189], v[218:221], v[20:23]
	v_mfma_f32_16x16x32_bf16 v[16:19], v[194:197], v[218:221], v[16:19]
	v_mfma_f32_16x16x32_bf16 v[4:7], v[186:189], v[226:229], v[4:7]
	v_mfma_f32_16x16x32_bf16 v[0:3], v[194:197], v[226:229], v[0:3]
	v_mfma_f32_16x16x32_bf16 v[52:55], v[190:193], v[206:209], v[52:55]
	v_mfma_f32_16x16x32_bf16 v[48:51], v[198:201], v[206:209], v[48:51]
	v_mfma_f32_16x16x32_bf16 v[36:39], v[190:193], v[214:217], v[36:39]
	v_mfma_f32_16x16x32_bf16 v[32:35], v[198:201], v[214:217], v[32:35]
	v_mfma_f32_16x16x32_bf16 v[20:23], v[190:193], v[222:225], v[20:23]
	v_mfma_f32_16x16x32_bf16 v[16:19], v[198:201], v[222:225], v[16:19]
	v_mfma_f32_16x16x32_bf16 v[4:7], v[190:193], v[230:233], v[4:7]
	v_mfma_f32_16x16x32_bf16 v[0:3], v[198:201], v[230:233], v[0:3]
	s_setprio 0
	s_barrier
	s_add_i32 s33, s33, 2
	s_add_u32 s4, s4, 0x100
	s_addc_u32 s5, s5, 0
	s_add_u32 s30, s30, 0x100
	s_addc_u32 s31, s31, 0
	s_cmp_gt_u32 s33, 13
	s_cbranch_scc0 .LBB0_232
	s_and_b64 vcc, exec, s[12:13]
	s_cbranch_vccz .LBB0_235
	s_barrier

;     __device__ __forceinline__ void operator()(const pg8::f32x4 (&acc)[2][2][4][2], const pg8::Unit& u, int wr, int wc, int fr, int fq) const {
;     ...
;         float* fdst = nullptr; unsigned frow0 = 0;
;         if (kv) {
;             if (smp) { fdst = out + (grp == 0 ? (kind == 1 ? O_AKS : O_AVS) : (kind == 1 ? O_BKS : O_BVS)); }
;             else if (grp == 1) { fdst = out + (kind == 1 ? O_BKP : O_BVP); frow0 = (unsigned)u.pm * 256u; }
;             else if ((u.pm & 7) >= 6) { fdst = out + (kind == 1 ? O_AKP : O_AVP); frow0 = (unsigned)(u.pm >> 3) * 512u + (unsigned)((u.pm & 7) - 6) * 256u; }
;         }
;         const int hd0 = (u.pn & 1) * 4 + (wc >> 1), dcol = (wc & 1) * 32 + 8 * fq;
;         const unsigned bat = (unsigned)(u.pm >> 3), t0 = (unsigned)(u.pm & 7) * 256u;
; #pragma unroll
;         for (int ai = 0; ai < 2; ++ai)
; #pragma unroll
;             for (int m = 0; m < 4; ++m) {
;                 const int rt = ai * 128 + wr * 64 + m * 16 + fr;
; #pragma unroll
;                 for (int bj = 0; bj < 2; ++bj) {
;                     const unsigned head = (unsigned)(hd0 + 2 * bj);
;                     const unsigned bidx = sL ? ((((unsigned)(rt >> 5) * 8u + head) * (unsigned)sL + (unsigned)(sP + (rt & 31))) * 64u + (unsigned)dcol)
;                                              : (((bat * 8u + head) * 2048u + t0 + (unsigned)rt) * 64u + (unsigned)dcol);
;                     pg8::f32x4 v0 = acc[ai][bj][m][0], v1 = acc[ai][bj][m][1];
;                     if (fdst) { float* fp = fdst + ((frow0 + (unsigned)rt) * 512u + (unsigned)(colw + bj * 128)); *(pg8::f32x4*)fp = v0; *(pg8::f32x4*)(fp + 4) = v1; }
.LBB0_253:
	s_lshl_b32 s6, s6, 8
	s_and_b32 s31, s6, 0x100
	s_cmp_lg_u64 s[26:27], 0
	v_add_lshl_u32 v128, s67, v157, 9
	s_cselect_b64 s[28:29], -1, 0
	s_cselect_b32 s32, 56, 24
	s_cmp_eq_u64 s[26:27], 0
	v_or3_b32 v154, v128, v166, s31
	s_cbranch_scc1 .LBB0_255
	v_mov_b32_e32 v155, v145
	v_lshl_add_u64 v[128:129], v[154:155], 2, s[26:27]
	global_store_dwordx4 v[128:129], v[124:127], off
	global_store_dwordx4 v[128:129], v[120:123], off offset:16

; #define PG8_STAGE(bufoff, gbase, voff) do { _Pragma("unroll") for (int _i = 0; _i < 2; ++_i) \
;         __builtin_amdgcn_global_load_lds((const unsigned*)((const char*)(gbase) + (voff)[_i]), (PG8_LAS unsigned*)(lds + (bufoff) + ldsw + _i * 8192), 16, 0, 0); } while (0)
; #define PG8_WAIT_V(n) asm volatile("s_waitcnt vmcnt(" #n ")" ::: "memory")
; #define PG8_BAR __builtin_amdgcn_s_barrier()
; template <class Epi, class Sched, bool ALIGN_EPI = false, bool SP2 = false>
; __device__ __forceinline__ void gemm_phase(PG8_LAS unsigned char* lds, const Gemm g, const Sched& S, const Epi& E, const int tid) {
;     ...
;         PG8_STAGE(PG8_SB(1, 0), cB + kstep, voffB); PG8_STAGE(PG8_SA(1, 0), cA + kstep, voffA); PG8_STAGE(PG8_SB(1, 1), cB + hstep + kstep, voffB);
;         PG8_WAIT_V(6); PG8_BAR;
.LBB0_724:
	s_lshl_b32 s8, s8, 5
	s_and_b32 s16, s8, 0x60
	s_mov_b64 s[8:9], 0x80
	s_add_i32 m0, s13, 0x18000
	v_lshl_add_u64 v[6:7], v[6:7], 0, s[8:9]
	s_lshl_b32 s11, s1, 13
	s_lshl_b32 s17, s16, 7
	s_waitcnt vmcnt(2)
	s_barrier
	global_load_lds_dwordx4 v[6:7], off
	v_lshl_add_u64 v[4:5], v[4:5], 0, s[8:9]
	s_add_i32 m0, s13, 0x1a000
	s_add_i32 s33, s13, 0x8000
	s_add_i32 s34, s13, 0xa000
	global_load_lds_dwordx4 v[4:5], off
	v_lshl_add_u64 v[0:1], v[0:1], 0, s[8:9]
	s_mov_b32 m0, s33
	s_add_u32 s14, s24, 0x40080
	global_load_lds_dwordx4 v[0:1], off
	v_lshl_add_u64 v[0:1], v[2:3], 0, s[8:9]
	s_mov_b32 m0, s34
	s_addc_u32 s15, s25, 0
	global_load_lds_dwordx4 v[0:1], off
	s_add_i32 m0, s13, 0x1c000
	v_lshl_add_u64 v[0:1], s[14:15], 0, v[130:131]
	global_load_lds_dwordx4 v[0:1], off
	v_lshl_add_u64 v[0:1], s[14:15], 0, v[134:135]
	s_add_i32 m0, s13, 0x1e000
	v_lshlrev_b32_e32 v2, 2, v8
	global_load_lds_dwordx4 v[0:1], off
	v_lshrrev_b32_e32 v0, 1, v20
	v_and_b32_e32 v0, 24, v0
	v_lshlrev_b32_e32 v1, 6, v8
	v_lshl_or_b32 v1, v0, 1, v1
	v_and_b32_e32 v2, 32, v2
	v_or_b32_e32 v151, s16, v0
	v_lshlrev_b32_e32 v0, 14, v9
	v_bitop3_b32 v3, s11, v1, v2 bitop3:0xf6
	v_bitop3_b32 v146, s17, v1, v2 bitop3:0xf6
	v_lshlrev_b32_e32 v1, 10, v8
	v_and_b32_e32 v0, 0xffff8000, v0
	v_lshl_or_b32 v147, s1, 16, v1
	v_lshl_add_u32 v0, v10, 11, v0
	v_and_b32_e32 v1, 1, v9
	v_lshl_or_b32 v0, v1, 6, v0
	v_lshl_add_u32 v138, v11, 1, v0
	v_lshlrev_b32_e32 v0, 14, v12
	v_and_b32_e32 v0, 0xffff8000, v0
	s_waitcnt vmcnt(6)
	s_cmpk_lt_u32 s10, 0x100
	v_lshl_add_u32 v0, v13, 11, v0
	v_and_b32_e32 v1, 1, v12
	s_cselect_b64 s[10:11], -1, 0
	v_lshl_or_b32 v0, v1, 6, v0
	s_add_i32 s37, 0, 0x10000
	s_add_i32 s38, 0, 0x14000
	s_sext_i32_i8 s39, s0
	v_or_b32_e32 v148, 0x4000, v147
	v_or_b32_e32 v149, 0x8000, v147
	v_or_b32_e32 v150, 0xc000, v147
	s_ashr_i32 s35, s94, 31
	s_mov_b32 s36, s94
	v_mov_b32_e32 v139, v137
	v_lshl_add_u32 v140, v14, 1, v0
	v_mov_b32_e32 v141, v137
	v_mov_b64_e32 v[142:143], 0x400
	v_mov_b64_e32 v[144:145], 0x3ff
	v_add_u32_e32 v152, s37, v146
	v_add_u32_e32 v153, s38, v146
	v_add_u32_e32 v154, 0, v3
	s_barrier
	s_mov_b32 s32, 0
	s_branch .LBB0_727

; #define PG8_STAGE(bufoff, gbase, voff) do { _Pragma("unroll") for (int _i = 0; _i < 2; ++_i) \
;         __builtin_amdgcn_global_load_lds((const unsigned*)((const char*)(gbase) + (voff)[_i]), (PG8_LAS unsigned*)(lds + (bufoff) + ldsw + _i * 8192), 16, 0, 0); } while (0)
; #define PG8_LDA(dst, b, h) do { _Pragma("unroll") for (int m = 0; m < 4; ++m) _Pragma("unroll") for (int k = 0; k < 2; ++k) dst[m][k] = *(const PG8_LAS bf16x8*)(lds + PG8_SA(b, h) + aoff + m * 2048 + k * 1024); } while (0)
; #define PG8_LDB(dst, b, h) do { _Pragma("unroll") for (int n = 0; n < 2; ++n) _Pragma("unroll") for (int k = 0; k < 2; ++k) dst[n][k] = *(const PG8_LAS bf16x8*)(lds + PG8_SB(b, h) + boff + n * 2048 + k * 1024); } while (0)
; #define PG8_MMA(ai, bj, At, Bt) do { __builtin_amdgcn_s_setprio(1); _Pragma("unroll") for (int m = 0; m < 4; ++m) _Pragma("unroll") for (int n = 0; n < 2; ++n) _Pragma("unroll") for (int k = 0; k < 2; ++k) \
;         acc[ai][bj][m][n] = __builtin_amdgcn_mfma_f32_16x16x32_bf16(Bt[n][k], At[m][k], acc[ai][bj][m][n], 0, 0, 0); __builtin_amdgcn_s_setprio(0); } while (0)
; #define PG8_WAIT_V(n) asm volatile("s_waitcnt vmcnt(" #n ")" ::: "memory")
; #define PG8_WAIT_L(n) asm volatile("s_waitcnt lgkmcnt(" #n ")" ::: "memory")
; #define PG8_BAR __builtin_amdgcn_s_barrier()
; #define PG8_SCHED __builtin_amdgcn_sched_barrier(0)
; template <class Epi, class Sched, bool ALIGN_EPI = false, bool SP2 = false>
; __device__ __forceinline__ void gemm_phase(PG8_LAS unsigned char* lds, const Gemm g, const Sched& S, const Epi& E, const int tid) {
;     ...
;             PG8_LDB(B0, 0, 0); PG8_LDB(B1, 0, 1); PG8_SCHED; PG8_LDA(At, 0, 0); PG8_STAGE(PG8_SA(1, 1), a1 + hstep, voffA);
;             PG8_WAIT_V(8); PG8_WAIT_L(0); PG8_BAR; PG8_MMA(0, 0, At, B0); PG8_MMA(0, 1, At, B1); PG8_BAR; PG8_SCHED;
;             PG8_LDA(At, 0, 1); PG8_STAGE(PG8_SB(0, 0), b2, voffB); PG8_STAGE(PG8_SB(0, 1), b2 + hstep, voffB); PG8_STAGE(PG8_SA(0, 0), a2, voffA);
;             PG8_WAIT_V(8); PG8_WAIT_L(0); PG8_BAR; PG8_MMA(1, 0, At, B0); PG8_MMA(1, 1, At, B1); PG8_BAR; PG8_SCHED;
.LBB0_734:
	ds_read_b128 v[156:159], v152
	ds_read_b128 v[160:163], v152 offset:1024
	ds_read_b128 v[164:167], v152 offset:2048
	ds_read_b128 v[168:171], v152 offset:3072
	ds_read_b128 v[172:175], v153
	ds_read_b128 v[180:183], v153 offset:1024
	ds_read_b128 v[186:189], v153 offset:2048
	ds_read_b128 v[190:193], v153 offset:3072
	s_add_u32 s24, s22, 0xfffc0080
	s_addc_u32 s25, s23, -1
	s_cmp_eq_u32 s44, 12
	s_cselect_b32 s27, s17, s25
	s_cselect_b32 s26, s40, s24
	s_cselect_b32 s25, s15, s43
	s_cselect_b32 s24, s41, s42
	v_lshl_add_u64 v[176:177], s[22:23], 0, v[138:139]
	s_add_i32 m0, s13, 0xc000
	ds_read_b128 v[194:197], v154
	ds_read_b128 v[198:201], v154 offset:1024
	ds_read_b128 v[202:205], v154 offset:2048
	ds_read_b128 v[206:209], v154 offset:3072
	ds_read_b128 v[210:213], v154 offset:4096
	ds_read_b128 v[214:217], v154 offset:5120
	ds_read_b128 v[218:221], v154 offset:6144
	ds_read_b128 v[222:225], v154 offset:7168
	global_load_lds_dwordx4 v[176:177], off
	v_lshl_add_u64 v[176:177], s[22:23], 0, v[140:141]
	s_add_i32 m0, s13, 0xe000
	s_nop 0
	global_load_lds_dwordx4 v[176:177], off
	s_cmp_lg_u32 s32, 0
	s_cbranch_scc1 .Lg3w1_x
	s_waitcnt vmcnt(8)
.Lg3w1_j:
	s_waitcnt lgkmcnt(0)
	s_barrier
	s_setprio 1
	s_waitcnt lgkmcnt(0)
	v_mfma_f32_16x16x32_bf16 v[124:127], v[156:159], v[194:197], v[124:127]
	v_mfma_f32_16x16x32_bf16 v[120:123], v[164:167], v[194:197], v[120:123]
	v_mfma_f32_16x16x32_bf16 v[116:119], v[156:159], v[202:205], v[116:119]
	v_mfma_f32_16x16x32_bf16 v[112:115], v[164:167], v[202:205], v[112:115]
	v_mfma_f32_16x16x32_bf16 v[100:103], v[156:159], v[210:213], v[100:103]
	v_mfma_f32_16x16x32_bf16 v[96:99], v[164:167], v[210:213], v[96:99]
	v_mfma_f32_16x16x32_bf16 v[84:87], v[156:159], v[218:221], v[84:87]
	v_mfma_f32_16x16x32_bf16 v[80:83], v[164:167], v[218:221], v[80:83]
	v_mfma_f32_16x16x32_bf16 v[124:127], v[160:163], v[198:201], v[124:127]
	v_mfma_f32_16x16x32_bf16 v[120:123], v[168:171], v[198:201], v[120:123]
	v_mfma_f32_16x16x32_bf16 v[116:119], v[160:163], v[206:209], v[116:119]
	v_mfma_f32_16x16x32_bf16 v[112:115], v[168:171], v[206:209], v[112:115]
	v_mfma_f32_16x16x32_bf16 v[100:103], v[160:163], v[214:217], v[100:103]
	v_mfma_f32_16x16x32_bf16 v[96:99], v[168:171], v[214:217], v[96:99]
	v_mfma_f32_16x16x32_bf16 v[84:87], v[160:163], v[222:225], v[84:87]
	v_mfma_f32_16x16x32_bf16 v[80:83], v[168:171], v[222:225], v[80:83]
	s_setprio 0
	s_setprio 1
	v_mfma_f32_16x16x32_bf16 v[108:111], v[172:175], v[194:197], v[108:111]
	v_mfma_f32_16x16x32_bf16 v[104:107], v[186:189], v[194:197], v[104:107]
	v_mfma_f32_16x16x32_bf16 v[92:95], v[172:175], v[202:205], v[92:95]
	v_mfma_f32_16x16x32_bf16 v[88:91], v[186:189], v[202:205], v[88:91]
	v_mfma_f32_16x16x32_bf16 v[76:79], v[172:175], v[210:213], v[76:79]
	v_mfma_f32_16x16x32_bf16 v[72:75], v[186:189], v[210:213], v[72:75]
	v_mfma_f32_16x16x32_bf16 v[68:71], v[172:175], v[218:221], v[68:71]
	v_mfma_f32_16x16x32_bf16 v[64:67], v[186:189], v[218:221], v[64:67]
	v_mfma_f32_16x16x32_bf16 v[108:111], v[180:183], v[198:201], v[108:111]
	v_mfma_f32_16x16x32_bf16 v[104:107], v[190:193], v[198:201], v[104:107]
	v_mfma_f32_16x16x32_bf16 v[92:95], v[180:183], v[206:209], v[92:95]
	v_mfma_f32_16x16x32_bf16 v[88:91], v[190:193], v[206:209], v[88:91]
	v_mfma_f32_16x16x32_bf16 v[76:79], v[180:183], v[214:217], v[76:79]
	v_mfma_f32_16x16x32_bf16 v[72:75], v[190:193], v[214:217], v[72:75]
	v_mfma_f32_16x16x32_bf16 v[68:71], v[180:183], v[222:225], v[68:71]
	v_mfma_f32_16x16x32_bf16 v[64:67], v[190:193], v[222:225], v[64:67]
	s_setprio 0
	s_barrier
	s_add_i32 s45, s37, s3
	v_lshl_add_u64 v[176:177], s[24:25], 0, v[130:131]
	s_mov_b32 m0, s45
	ds_read_b128 v[194:197], v154 offset:16384
	ds_read_b128 v[198:201], v154 offset:17408
	ds_read_b128 v[202:205], v154 offset:18432
	ds_read_b128 v[206:209], v154 offset:19456
	ds_read_b128 v[210:213], v154 offset:20480
	ds_read_b128 v[214:217], v154 offset:21504
	ds_read_b128 v[218:221], v154 offset:22528
	ds_read_b128 v[222:225], v154 offset:23552
	global_load_lds_dwordx4 v[176:177], off
	s_add_i32 m0, s45, 0x2000
	s_add_u32 s46, s24, 0x40000
	v_lshl_add_u64 v[226:227], s[24:25], 0, v[134:135]
	s_addc_u32 s47, s25, 0
	s_add_i32 s45, s38, s3
	global_load_lds_dwordx4 v[226:227], off
	v_lshl_add_u64 v[228:229], s[46:47], 0, v[130:131]
	s_mov_b32 m0, s45
	v_lshl_add_u64 v[230:231], s[26:27], 0, v[132:133]
	global_load_lds_dwordx4 v[228:229], off
	v_lshl_add_u64 v[228:229], s[46:47], 0, v[134:135]
	s_add_i32 m0, s45, 0x2000
	s_nop 0
	global_load_lds_dwordx4 v[228:229], off
	v_lshl_add_u64 v[228:229], s[26:27], 0, v[128:129]
	s_mov_b32 m0, s13
	s_nop 0
	global_load_lds_dwordx4 v[228:229], off
	s_mov_b32 m0, s28
	s_nop 0
	global_load_lds_dwordx4 v[230:231], off
	s_cmp_lg_u32 s32, 0
	s_cbranch_scc1 .Lg3w2_x
	s_waitcnt vmcnt(8)
; #define PG8_STAGE(bufoff, gbase, voff) do { _Pragma("unroll") for (int _i = 0; _i < 2; ++_i) \
;         __builtin_amdgcn_global_load_lds((const unsigned*)((const char*)(gbase) + (voff)[_i]), (PG8_LAS unsigned*)(lds + (bufoff) + ldsw + _i * 8192), 16, 0, 0); } while (0)
; #define PG8_LDA(dst, b, h) do { _Pragma("unroll") for (int m = 0; m < 4; ++m) _Pragma("unroll") for (int k = 0; k < 2; ++k) dst[m][k] = *(const PG8_LAS bf16x8*)(lds + PG8_SA(b, h) + aoff + m * 2048 + k * 1024); } while (0)
; #define PG8_LDB(dst, b, h) do { _Pragma("unroll") for (int n = 0; n < 2; ++n) _Pragma("unroll") for (int k = 0; k < 2; ++k) dst[n][k] = *(const PG8_LAS bf16x8*)(lds + PG8_SB(b, h) + boff + n * 2048 + k * 1024); } while (0)
; #define PG8_MMA(ai, bj, At, Bt) do { __builtin_amdgcn_s_setprio(1); _Pragma("unroll") for (int m = 0; m < 4; ++m) _Pragma("unroll") for (int n = 0; n < 2; ++n) _Pragma("unroll") for (int k = 0; k < 2; ++k) \
;         acc[ai][bj][m][n] = __builtin_amdgcn_mfma_f32_16x16x32_bf16(Bt[n][k], At[m][k], acc[ai][bj][m][n], 0, 0, 0); __builtin_amdgcn_s_setprio(0); } while (0)
; #define PG8_WAIT_V(n) asm volatile("s_waitcnt vmcnt(" #n ")" ::: "memory")
; #define PG8_WAIT_L(n) asm volatile("s_waitcnt lgkmcnt(" #n ")" ::: "memory")
; #define PG8_BAR __builtin_amdgcn_s_barrier()
; #define PG8_SCHED __builtin_amdgcn_sched_barrier(0)
; template <class Epi, class Sched, bool ALIGN_EPI = false, bool SP2 = false>
; __device__ __forceinline__ void gemm_phase(PG8_LAS unsigned char* lds, const Gemm g, const Sched& S, const Epi& E, const int tid) {
;     ...
;             PG8_WAIT_V(8); PG8_WAIT_L(0); PG8_BAR; PG8_MMA(1, 0, At, B0); PG8_MMA(1, 1, At, B1); PG8_BAR; PG8_SCHED;
;             PG8_LDB(B0, 1, 0); PG8_LDB(B1, 1, 1); PG8_SCHED; PG8_LDA(At, 1, 0); PG8_STAGE(PG8_SA(0, 1), a2 + hstep, voffA);
;             PG8_WAIT_V(8); PG8_WAIT_L(0); PG8_BAR; PG8_MMA(0, 0, At, B0); PG8_MMA(0, 1, At, B1); PG8_BAR; PG8_SCHED;
.Lg3w2_j:
	s_waitcnt lgkmcnt(0)
	s_barrier
	s_setprio 1
	s_waitcnt lgkmcnt(0)
	v_mfma_f32_16x16x32_bf16 v[60:63], v[156:159], v[194:197], v[60:63]
	v_mfma_f32_16x16x32_bf16 v[56:59], v[164:167], v[194:197], v[56:59]
	v_mfma_f32_16x16x32_bf16 v[52:55], v[156:159], v[202:205], v[52:55]
	v_mfma_f32_16x16x32_bf16 v[48:51], v[164:167], v[202:205], v[48:51]
	v_mfma_f32_16x16x32_bf16 v[36:39], v[156:159], v[210:213], v[36:39]
	v_mfma_f32_16x16x32_bf16 v[32:35], v[164:167], v[210:213], v[32:35]
	v_mfma_f32_16x16x32_bf16 v[20:23], v[156:159], v[218:221], v[20:23]
	v_mfma_f32_16x16x32_bf16 v[16:19], v[164:167], v[218:221], v[16:19]
	v_mfma_f32_16x16x32_bf16 v[60:63], v[160:163], v[198:201], v[60:63]
	v_mfma_f32_16x16x32_bf16 v[56:59], v[168:171], v[198:201], v[56:59]
	v_mfma_f32_16x16x32_bf16 v[52:55], v[160:163], v[206:209], v[52:55]
	v_mfma_f32_16x16x32_bf16 v[48:51], v[168:171], v[206:209], v[48:51]
	v_mfma_f32_16x16x32_bf16 v[36:39], v[160:163], v[214:217], v[36:39]
	v_mfma_f32_16x16x32_bf16 v[32:35], v[168:171], v[214:217], v[32:35]
	v_mfma_f32_16x16x32_bf16 v[20:23], v[160:163], v[222:225], v[20:23]
	v_mfma_f32_16x16x32_bf16 v[16:19], v[168:171], v[222:225], v[16:19]
	s_setprio 0
	s_setprio 1
	v_mfma_f32_16x16x32_bf16 v[44:47], v[172:175], v[194:197], v[44:47]
	v_mfma_f32_16x16x32_bf16 v[40:43], v[186:189], v[194:197], v[40:43]
	v_mfma_f32_16x16x32_bf16 v[28:31], v[172:175], v[202:205], v[28:31]
	v_mfma_f32_16x16x32_bf16 v[24:27], v[186:189], v[202:205], v[24:27]
	v_mfma_f32_16x16x32_bf16 v[12:15], v[172:175], v[210:213], v[12:15]
	v_mfma_f32_16x16x32_bf16 v[8:11], v[186:189], v[210:213], v[8:11]
	v_mfma_f32_16x16x32_bf16 v[4:7], v[172:175], v[218:221], v[4:7]
	v_mfma_f32_16x16x32_bf16 v[0:3], v[186:189], v[218:221], v[0:3]
	v_mfma_f32_16x16x32_bf16 v[44:47], v[180:183], v[198:201], v[44:47]
	v_mfma_f32_16x16x32_bf16 v[40:43], v[190:193], v[198:201], v[40:43]
	v_mfma_f32_16x16x32_bf16 v[28:31], v[180:183], v[206:209], v[28:31]
	v_mfma_f32_16x16x32_bf16 v[24:27], v[190:193], v[206:209], v[24:27]
	v_mfma_f32_16x16x32_bf16 v[12:15], v[180:183], v[214:217], v[12:15]
	v_mfma_f32_16x16x32_bf16 v[8:11], v[190:193], v[214:217], v[8:11]
	v_mfma_f32_16x16x32_bf16 v[4:7], v[180:183], v[222:225], v[4:7]
	v_mfma_f32_16x16x32_bf16 v[0:3], v[190:193], v[222:225], v[0:3]
	s_setprio 0
	s_barrier
	s_add_i32 s45, 0, 0x18000
	v_add_u32_e32 v136, s45, v146
	s_add_i32 s46, 0, 0x1c000
	ds_read_b128 v[156:159], v136
	ds_read_b128 v[160:163], v136 offset:1024
	ds_read_b128 v[164:167], v136 offset:2048
	ds_read_b128 v[168:171], v136 offset:3072
	v_add_u32_e32 v136, s46, v146
	ds_read_b128 v[172:175], v136
	ds_read_b128 v[180:183], v136 offset:1024
	ds_read_b128 v[186:189], v136 offset:2048
	ds_read_b128 v[190:193], v136 offset:3072
	s_add_u32 s26, s26, 0x40000
	s_addc_u32 s27, s27, 0
	s_mov_b32 m0, s29
	v_lshl_add_u64 v[232:233], s[26:27], 0, v[128:129]
	ds_read_b128 v[194:197], v154 offset:32768
	ds_read_b128 v[198:201], v154 offset:33792
	ds_read_b128 v[202:205], v154 offset:34816
	ds_read_b128 v[206:209], v154 offset:35840
	ds_read_b128 v[210:213], v154 offset:36864
	ds_read_b128 v[214:217], v154 offset:37888
	ds_read_b128 v[218:221], v154 offset:38912
	ds_read_b128 v[222:225], v154 offset:39936
	global_load_lds_dwordx4 v[232:233], off
	v_lshl_add_u64 v[232:233], s[26:27], 0, v[132:133]
	s_mov_b32 m0, s30
	s_nop 0
	global_load_lds_dwordx4 v[232:233], off
	s_waitcnt vmcnt(8)
	s_waitcnt lgkmcnt(0)
	s_barrier
	s_setprio 1
	s_waitcnt lgkmcnt(0)
	v_mfma_f32_16x16x32_bf16 v[124:127], v[156:159], v[194:197], v[124:127]
	v_mfma_f32_16x16x32_bf16 v[120:123], v[164:167], v[194:197], v[120:123]
	v_mfma_f32_16x16x32_bf16 v[116:119], v[156:159], v[202:205], v[116:119]
	v_mfma_f32_16x16x32_bf16 v[112:115], v[164:167], v[202:205], v[112:115]
	v_mfma_f32_16x16x32_bf16 v[100:103], v[156:159], v[210:213], v[100:103]
	v_mfma_f32_16x16x32_bf16 v[96:99], v[164:167], v[210:213], v[96:99]
	v_mfma_f32_16x16x32_bf16 v[84:87], v[156:159], v[218:221], v[84:87]
	v_mfma_f32_16x16x32_bf16 v[80:83], v[164:167], v[218:221], v[80:83]
	v_mfma_f32_16x16x32_bf16 v[124:127], v[160:163], v[198:201], v[124:127]
	v_mfma_f32_16x16x32_bf16 v[120:123], v[168:171], v[198:201], v[120:123]
	v_mfma_f32_16x16x32_bf16 v[116:119], v[160:163], v[206:209], v[116:119]
	v_mfma_f32_16x16x32_bf16 v[112:115], v[168:171], v[206:209], v[112:115]
	v_mfma_f32_16x16x32_bf16 v[100:103], v[160:163], v[214:217], v[100:103]
	v_mfma_f32_16x16x32_bf16 v[96:99], v[168:171], v[214:217], v[96:99]
	v_mfma_f32_16x16x32_bf16 v[84:87], v[160:163], v[222:225], v[84:87]
	v_mfma_f32_16x16x32_bf16 v[80:83], v[168:171], v[222:225], v[80:83]
	s_setprio 0
	s_setprio 1
	v_mfma_f32_16x16x32_bf16 v[108:111], v[172:175], v[194:197], v[108:111]
	v_mfma_f32_16x16x32_bf16 v[104:107], v[186:189], v[194:197], v[104:107]
	v_mfma_f32_16x16x32_bf16 v[92:95], v[172:175], v[202:205], v[92:95]
	v_mfma_f32_16x16x32_bf16 v[88:91], v[186:189], v[202:205], v[88:91]
	v_mfma_f32_16x16x32_bf16 v[76:79], v[172:175], v[210:213], v[76:79]
	v_mfma_f32_16x16x32_bf16 v[72:75], v[186:189], v[210:213], v[72:75]
	v_mfma_f32_16x16x32_bf16 v[68:71], v[172:175], v[218:221], v[68:71]
	v_mfma_f32_16x16x32_bf16 v[64:67], v[186:189], v[218:221], v[64:67]
	v_mfma_f32_16x16x32_bf16 v[108:111], v[180:183], v[198:201], v[108:111]
	v_mfma_f32_16x16x32_bf16 v[104:107], v[190:193], v[198:201], v[104:107]
	v_mfma_f32_16x16x32_bf16 v[92:95], v[180:183], v[206:209], v[92:95]
	v_mfma_f32_16x16x32_bf16 v[88:91], v[190:193], v[206:209], v[88:91]
	v_mfma_f32_16x16x32_bf16 v[76:79], v[180:183], v[214:217], v[76:79]
	v_mfma_f32_16x16x32_bf16 v[72:75], v[190:193], v[214:217], v[72:75]
	v_mfma_f32_16x16x32_bf16 v[68:71], v[180:183], v[222:225], v[68:71]
	v_mfma_f32_16x16x32_bf16 v[64:67], v[190:193], v[222:225], v[64:67]
	s_setprio 0
	s_barrier
; #define PG8_STAGE(bufoff, gbase, voff) do { _Pragma("unroll") for (int _i = 0; _i < 2; ++_i) \
;         __builtin_amdgcn_global_load_lds((const unsigned*)((const char*)(gbase) + (voff)[_i]), (PG8_LAS unsigned*)(lds + (bufoff) + ldsw + _i * 8192), 16, 0, 0); } while (0)
; #define PG8_LDA(dst, b, h) do { _Pragma("unroll") for (int m = 0; m < 4; ++m) _Pragma("unroll") for (int k = 0; k < 2; ++k) dst[m][k] = *(const PG8_LAS bf16x8*)(lds + PG8_SA(b, h) + aoff + m * 2048 + k * 1024); } while (0)
; #define PG8_MMA(ai, bj, At, Bt) do { __builtin_amdgcn_s_setprio(1); _Pragma("unroll") for (int m = 0; m < 4; ++m) _Pragma("unroll") for (int n = 0; n < 2; ++n) _Pragma("unroll") for (int k = 0; k < 2; ++k) \
;         acc[ai][bj][m][n] = __builtin_amdgcn_mfma_f32_16x16x32_bf16(Bt[n][k], At[m][k], acc[ai][bj][m][n], 0, 0, 0); __builtin_amdgcn_s_setprio(0); } while (0)
; #define PG8_WAIT_V(n) asm volatile("s_waitcnt vmcnt(" #n ")" ::: "memory")
; #define PG8_WAIT_L(n) asm volatile("s_waitcnt lgkmcnt(" #n ")" ::: "memory")
; #define PG8_BAR __builtin_amdgcn_s_barrier()
; #define PG8_SCHED __builtin_amdgcn_sched_barrier(0)
; template <class Epi, class Sched, bool ALIGN_EPI = false, bool SP2 = false>
; __device__ __forceinline__ void gemm_phase(PG8_LAS unsigned char* lds, const Gemm g, const Sched& S, const Epi& E, const int tid) {
;     ...
;         for (int t = 0; t < nt; t += 2) {
;     ...
;             PG8_LDA(At, 1, 1); PG8_STAGE(PG8_SB(1, 0), b3, voffB); PG8_STAGE(PG8_SB(1, 1), b3 + hstep, voffB); PG8_STAGE(PG8_SA(1, 0), a3, voffA);
;             PG8_WAIT_V(8); PG8_WAIT_L(0); PG8_BAR; PG8_MMA(1, 0, At, B0); PG8_MMA(1, 1, At, B1); PG8_BAR; PG8_SCHED;
	s_add_i32 s26, s45, s3
	v_lshl_add_u64 v[176:177], v[176:177], 0, s[8:9]
	s_mov_b32 m0, s26
	ds_read_b128 v[194:197], v154 offset:49152
	ds_read_b128 v[198:201], v154 offset:50176
	ds_read_b128 v[202:205], v154 offset:51200
	ds_read_b128 v[206:209], v154 offset:52224
	ds_read_b128 v[210:213], v154 offset:53248
	ds_read_b128 v[214:217], v154 offset:54272
	ds_read_b128 v[218:221], v154 offset:55296
	ds_read_b128 v[222:225], v154 offset:56320
	global_load_lds_dwordx4 v[176:177], off
	s_add_i32 m0, s26, 0x2000
	s_add_u32 s24, s24, 0x40080
	v_lshl_add_u64 v[176:177], v[226:227], 0, s[8:9]
	s_addc_u32 s25, s25, 0
	s_add_i32 s26, s46, s3
	global_load_lds_dwordx4 v[176:177], off
	v_lshl_add_u64 v[176:177], s[24:25], 0, v[130:131]
	s_mov_b32 m0, s26
	s_nop 0
	global_load_lds_dwordx4 v[176:177], off
	v_lshl_add_u64 v[176:177], s[24:25], 0, v[134:135]
	s_add_i32 m0, s26, 0x2000
	s_nop 0
	global_load_lds_dwordx4 v[176:177], off
	v_lshl_add_u64 v[176:177], v[228:229], 0, s[8:9]
	s_mov_b32 m0, s33
	s_nop 0
	global_load_lds_dwordx4 v[176:177], off
	v_lshl_add_u64 v[176:177], v[230:231], 0, s[8:9]
	s_mov_b32 m0, s34
	s_nop 0
	global_load_lds_dwordx4 v[176:177], off
	s_waitcnt vmcnt(8)
	s_waitcnt lgkmcnt(0)
	s_barrier
	s_setprio 1
	s_waitcnt lgkmcnt(0)
	v_mfma_f32_16x16x32_bf16 v[60:63], v[156:159], v[194:197], v[60:63]
	v_mfma_f32_16x16x32_bf16 v[56:59], v[164:167], v[194:197], v[56:59]
	v_mfma_f32_16x16x32_bf16 v[52:55], v[156:159], v[202:205], v[52:55]
	v_mfma_f32_16x16x32_bf16 v[48:51], v[164:167], v[202:205], v[48:51]
	v_mfma_f32_16x16x32_bf16 v[36:39], v[156:159], v[210:213], v[36:39]
	v_mfma_f32_16x16x32_bf16 v[32:35], v[164:167], v[210:213], v[32:35]
	v_mfma_f32_16x16x32_bf16 v[20:23], v[156:159], v[218:221], v[20:23]
	v_mfma_f32_16x16x32_bf16 v[16:19], v[164:167], v[218:221], v[16:19]
	v_mfma_f32_16x16x32_bf16 v[60:63], v[160:163], v[198:201], v[60:63]
	v_mfma_f32_16x16x32_bf16 v[56:59], v[168:171], v[198:201], v[56:59]
	v_mfma_f32_16x16x32_bf16 v[52:55], v[160:163], v[206:209], v[52:55]
	v_mfma_f32_16x16x32_bf16 v[48:51], v[168:171], v[206:209], v[48:51]
	v_mfma_f32_16x16x32_bf16 v[36:39], v[160:163], v[214:217], v[36:39]
	v_mfma_f32_16x16x32_bf16 v[32:35], v[168:171], v[214:217], v[32:35]
	v_mfma_f32_16x16x32_bf16 v[20:23], v[160:163], v[222:225], v[20:23]
	v_mfma_f32_16x16x32_bf16 v[16:19], v[168:171], v[222:225], v[16:19]
	s_setprio 0
	s_setprio 1
	v_mfma_f32_16x16x32_bf16 v[44:47], v[172:175], v[194:197], v[44:47]
	v_mfma_f32_16x16x32_bf16 v[40:43], v[186:189], v[194:197], v[40:43]
	v_mfma_f32_16x16x32_bf16 v[28:31], v[172:175], v[202:205], v[28:31]
	v_mfma_f32_16x16x32_bf16 v[24:27], v[186:189], v[202:205], v[24:27]
	v_mfma_f32_16x16x32_bf16 v[12:15], v[172:175], v[210:213], v[12:15]
	v_mfma_f32_16x16x32_bf16 v[8:11], v[186:189], v[210:213], v[8:11]
	v_mfma_f32_16x16x32_bf16 v[4:7], v[172:175], v[218:221], v[4:7]
	v_mfma_f32_16x16x32_bf16 v[0:3], v[186:189], v[218:221], v[0:3]
	v_mfma_f32_16x16x32_bf16 v[44:47], v[180:183], v[198:201], v[44:47]
	v_mfma_f32_16x16x32_bf16 v[40:43], v[190:193], v[198:201], v[40:43]
	v_mfma_f32_16x16x32_bf16 v[28:31], v[180:183], v[206:209], v[28:31]
	v_mfma_f32_16x16x32_bf16 v[24:27], v[190:193], v[206:209], v[24:27]
	v_mfma_f32_16x16x32_bf16 v[12:15], v[180:183], v[214:217], v[12:15]
	v_mfma_f32_16x16x32_bf16 v[8:11], v[190:193], v[214:217], v[8:11]
	v_mfma_f32_16x16x32_bf16 v[4:7], v[180:183], v[222:225], v[4:7]
	v_mfma_f32_16x16x32_bf16 v[0:3], v[190:193], v[222:225], v[0:3]
	s_setprio 0
	s_barrier
	s_add_i32 s44, s44, 2
	s_add_u32 s22, s22, 0x100
	s_addc_u32 s23, s23, 0
	s_add_u32 s42, s42, 0x100
	s_addc_u32 s43, s43, 0
	s_cmp_gt_u32 s44, 13
	s_cbranch_scc0 .LBB0_734
	s_and_b64 vcc, exec, s[10:11]
	s_cbranch_vccz .LBB0_737
	s_barrier
; __device__ __forceinline__ unsigned pk2(float lo, float hi) { f32x2_t v = {lo, hi}; bf16x2_t b = __builtin_convertvector(v, bf16x2_t); return __builtin_bit_cast(unsigned, b); }
;     __device__ __forceinline__ void operator()(const pg8::f32x4 (&acc)[2][2][4][2], const pg8::Unit& u, int wr, int wc, int fr, int fq) const {
;         const unsigned c0 = (unsigned)(u.pn * 256 + wc * 32 + 8 * fq);
; #pragma unroll
;         for (int ai = 0; ai < 2; ++ai)
; #pragma unroll
;             for (int m = 0; m < 4; ++m) {
;                 const unsigned grow = (unsigned)u.pm * 256u + (unsigned)(ai * 128 + wr * 64 + m * 16 + fr);
; #pragma unroll
;                 for (int bj = 0; bj < 2; ++bj) {
;                     const pg8::f32x4 v0 = acc[ai][bj][m][0], v1 = acc[ai][bj][m][1];
;                     pg8::u32x4 w; w.x = pk2(v0[0], v0[1]); w.y = pk2(v0[2], v0[3]); w.z = pk2(v1[0], v1[1]); w.w = pk2(v1[2], v1[3]);
;                     *(pg8::u32x4*)(mo + (grow * 1024u + c0 + (unsigned)(bj * 128))) = w;
;                 }
;             }
.LBB0_737:
	s_mov_b32 s32, 24
	s_lshl_b32 s15, s39, 8
	s_lshl_b32 s12, s12, 18
	s_add_i32 s12, s12, s15
	v_or_b32_e32 v155, s12, v151
	v_add_u32_e32 v136, v155, v147
	v_cvt_pk_bf16_f32 v108, v108, v109
	v_cvt_pk_bf16_f32 v109, v110, v111
	v_cvt_pk_bf16_f32 v110, v104, v105
	v_or_b32_e32 v104, 0x80, v136
	v_mov_b32_e32 v105, v137
	v_cvt_pk_bf16_f32 v111, v106, v107
	v_lshl_add_u64 v[104:105], v[104:105], 1, s[4:5]
	global_store_dwordx4 v[104:105], v[108:111], off
	v_cvt_pk_bf16_f32 v92, v92, v93
	v_cvt_pk_bf16_f32 v93, v94, v95
	v_add_u32_e32 v108, v155, v148
	v_cvt_pk_bf16_f32 v94, v88, v89
	v_or_b32_e32 v88, 0x80, v108
	v_mov_b32_e32 v89, v137
	v_cvt_pk_bf16_f32 v124, v124, v125
	v_cvt_pk_bf16_f32 v125, v126, v127
	v_cvt_pk_bf16_f32 v126, v120, v121
	v_cvt_pk_bf16_f32 v127, v122, v123
	v_lshl_add_u64 v[120:121], v[136:137], 1, s[4:5]
	v_cvt_pk_bf16_f32 v95, v90, v91
	v_lshl_add_u64 v[88:89], v[88:89], 1, s[4:5]
	global_store_dwordx4 v[120:121], v[124:127], off
	global_store_dwordx4 v[88:89], v[92:95], off
	v_mov_b32_e32 v109, v137
	v_cvt_pk_bf16_f32 v76, v76, v77
	v_add_u32_e32 v92, v155, v149
	v_cvt_pk_bf16_f32 v77, v78, v79
	v_cvt_pk_bf16_f32 v78, v72, v73
	v_or_b32_e32 v72, 0x80, v92
	v_mov_b32_e32 v73, v137
	v_cvt_pk_bf16_f32 v104, v116, v117
	v_cvt_pk_bf16_f32 v105, v118, v119
	v_cvt_pk_bf16_f32 v106, v112, v113
	v_cvt_pk_bf16_f32 v107, v114, v115
	v_lshl_add_u64 v[110:111], v[108:109], 1, s[4:5]
	v_cvt_pk_bf16_f32 v79, v74, v75
	v_lshl_add_u64 v[72:73], v[72:73], 1, s[4:5]
	global_store_dwordx4 v[110:111], v[104:107], off
	global_store_dwordx4 v[72:73], v[76:79], off
	v_mov_b32_e32 v93, v137
	v_cvt_pk_bf16_f32 v68, v68, v69
	v_add_u32_e32 v76, v155, v150
	v_mov_b32_e32 v77, v137
	v_cvt_pk_bf16_f32 v69, v70, v71
	v_cvt_pk_bf16_f32 v70, v64, v65
	v_or_b32_e32 v64, 0x80, v76
	v_mov_b32_e32 v65, v137
	v_cvt_pk_bf16_f32 v44, v44, v45
	v_cvt_pk_bf16_f32 v45, v46, v47
	v_cvt_pk_bf16_f32 v46, v40, v41
	v_add_u32_e32 v40, 0x20080, v136
	v_mov_b32_e32 v41, v137
	v_cvt_pk_bf16_f32 v28, v28, v29
	v_cvt_pk_bf16_f32 v29, v30, v31
	v_cvt_pk_bf16_f32 v30, v24, v25
	v_add_u32_e32 v24, 0x24080, v136
	v_mov_b32_e32 v25, v137
	v_cvt_pk_bf16_f32 v12, v12, v13
	v_cvt_pk_bf16_f32 v13, v14, v15
	v_cvt_pk_bf16_f32 v14, v8, v9
	v_add_u32_e32 v8, 0x28080, v136
	v_mov_b32_e32 v9, v137
	v_cvt_pk_bf16_f32 v88, v100, v101
	v_cvt_pk_bf16_f32 v89, v102, v103
	v_cvt_pk_bf16_f32 v90, v96, v97
	v_cvt_pk_bf16_f32 v91, v98, v99
	v_lshl_add_u64 v[94:95], v[92:93], 1, s[4:5]
	v_cvt_pk_bf16_f32 v72, v84, v85
	v_cvt_pk_bf16_f32 v73, v86, v87
	v_cvt_pk_bf16_f32 v74, v80, v81
	v_cvt_pk_bf16_f32 v75, v82, v83
	v_lshl_add_u64 v[78:79], v[76:77], 1, s[4:5]
	v_cvt_pk_bf16_f32 v71, v66, v67
	v_lshl_add_u64 v[64:65], v[64:65], 1, s[4:5]
	v_cvt_pk_bf16_f32 v47, v42, v43
	v_lshl_add_u64 v[40:41], v[40:41], 1, s[4:5]
	v_cvt_pk_bf16_f32 v31, v26, v27
	v_lshl_add_u64 v[24:25], v[24:25], 1, s[4:5]
	v_cvt_pk_bf16_f32 v15, v10, v11
	v_lshl_add_u64 v[8:9], v[8:9], 1, s[4:5]
	global_store_dwordx4 v[94:95], v[88:91], off
	global_store_dwordx4 v[78:79], v[72:75], off
	global_store_dwordx4 v[64:65], v[68:71], off
	v_add_u32_e32 v64, 0x20000, v136
	v_mov_b32_e32 v65, v137
	global_store_dwordx4 v[40:41], v[44:47], off
	global_store_dwordx4 v[24:25], v[28:31], off
	global_store_dwordx4 v[8:9], v[12:15], off
	v_add_u32_e32 v44, 0x24000, v136
	v_mov_b32_e32 v45, v137
	v_add_u32_e32 v28, 0x28000, v136
	v_mov_b32_e32 v29, v137
	v_add_u32_e32 v12, 0x2c000, v136
	v_mov_b32_e32 v13, v137
	v_add_u32_e32 v136, 0x2c080, v136
	v_cvt_pk_bf16_f32 v60, v60, v61
	v_cvt_pk_bf16_f32 v61, v62, v63
	v_cvt_pk_bf16_f32 v62, v56, v57
	v_cvt_pk_bf16_f32 v63, v58, v59
	v_lshl_add_u64 v[56:57], v[64:65], 1, s[4:5]
	v_cvt_pk_bf16_f32 v40, v52, v53
	v_cvt_pk_bf16_f32 v41, v54, v55
	v_cvt_pk_bf16_f32 v42, v48, v49
	v_cvt_pk_bf16_f32 v43, v50, v51
	v_lshl_add_u64 v[44:45], v[44:45], 1, s[4:5]
	v_cvt_pk_bf16_f32 v24, v36, v37
	v_cvt_pk_bf16_f32 v25, v38, v39
	v_cvt_pk_bf16_f32 v26, v32, v33
	v_cvt_pk_bf16_f32 v27, v34, v35
	v_lshl_add_u64 v[28:29], v[28:29], 1, s[4:5]
	v_cvt_pk_bf16_f32 v8, v20, v21
	v_cvt_pk_bf16_f32 v9, v22, v23
	v_cvt_pk_bf16_f32 v10, v16, v17
	v_cvt_pk_bf16_f32 v11, v18, v19
	v_lshl_add_u64 v[12:13], v[12:13], 1, s[4:5]
	v_cvt_pk_bf16_f32 v4, v4, v5
	v_cvt_pk_bf16_f32 v5, v6, v7
	v_cvt_pk_bf16_f32 v6, v0, v1
	v_cvt_pk_bf16_f32 v7, v2, v3
	v_lshl_add_u64 v[0:1], v[136:137], 1, s[4:5]
	s_andn2_b64 vcc, exec, s[0:1]
	s_mov_b64 s[0:1], -1
	global_store_dwordx4 v[56:57], v[60:63], off
	global_store_dwordx4 v[44:45], v[40:43], off
	global_store_dwordx4 v[28:29], v[24:27], off
	global_store_dwordx4 v[12:13], v[8:11], off
	global_store_dwordx4 v[0:1], v[4:7], off
	s_cbranch_vccnz .LBB0_726
	s_andn2_b64 vcc, exec, s[6:7]
	s_cbranch_vccnz .LBB0_725
	s_barrier
	s_branch .LBB0_725
